# gate/branch phase tile prologue: gate-bias and row-rstd loads issued together before a single wait
# speedup vs baseline: 1.0029x; 1.0029x over previous
; DEVI int get_tid512() { int t = threadIdx.x; asm volatile("" : "+v"(t)); return t; }
; DEVI float ssq_rstd(float v) { return rsqrtf(v * (1.f / 1024.f) + 1e-6f); }
; DEVI void phase4(const Params& p, int l, char* lds, float* p4s) {
;     ...
;     {
;       const int t = get_tid512();
;       p4s[t] = bg[(t >> 7) * 1024 + n0 + (t & 127)];
;       if (t < 256) {
;         const float4 q = *(const float4*)((const float*)(p.ws + OFF_SSQA) + (long)(m0 + t) * 4);
;         p4s[512 + t] = ssq_rstd((q.x + q.y) + (q.z + q.w));
;       }
;     }
.LBB0_406:
	v_mov_b32_e32 v2, v220
	s_lshl_b32 s60, s23, 7
	v_lshlrev_b32_e32 v0, 3, v2
	v_and_b32_e32 v0, 0xfffffc00, v0
	v_add_u32_e32 v0, s60, v0
	s_movk_i32 s21, 0x7f
	v_and_or_b32 v4, v2, s21, v0
	v_ashrrev_i32_e32 v5, 31, v4
	v_lshl_add_u64 v[4:5], v[4:5], 2, s[0:1]
	global_load_dword v3, v[4:5], off
	s_lshl_b32 s61, s20, 8
	v_lshlrev_b32_e32 v0, 2, v2
	v_cmp_gt_i32_e32 vcc, s94, v2
	s_and_saveexec_b64 s[36:37], vcc
	v_add_u32_e32 v250, s61, v2
	v_readlane_b32 s38, v244, 55
	v_ashrrev_i32_e32 v251, 31, v250
	v_readlane_b32 s39, v244, 56
	s_mov_b32 s21, 0x800000
	s_nop 0
	v_lshl_add_u64 v[250:251], v[250:251], 4, s[38:39]
	global_load_dwordx4 v[246:249], v[250:251], off
	s_or_b64 exec, exec, s[36:37]
	s_waitcnt vmcnt(0)
	ds_write_b32 v0, v3
	s_and_saveexec_b64 s[36:37], vcc
	s_cbranch_execz .LBB0_408
	v_mov_b32_e32 v2, v246
	v_mov_b32_e32 v6, v247
	v_mov_b32_e32 v7, v248
	v_mov_b32_e32 v3, v249
	v_pk_add_f32 v[2:3], v[6:7], v[2:3]
	s_nop 0
	v_add_f32_e32 v2, v2, v3
	v_fmamk_f32 v2, v2, 0x3a800000, v222
	v_mul_f32_e32 v3, 0x4b800000, v2
	v_cmp_gt_f32_e32 vcc, s21, v2
	s_nop 1
	v_cndmask_b32_e32 v2, v2, v3, vcc
	v_rsq_f32_e32 v2, v2
	s_nop 0
	v_mul_f32_e32 v3, 0x45800000, v2
	v_cndmask_b32_e32 v2, v2, v3, vcc
	ds_write_b32 v0, v2 offset:2048
